# new rw_phaseB with split counted waits: decay and R operands waited first, P operands only before the MFMAs; R and decay prefetch issued ahead of the MFMAs
# baseline (speedup 1.0000x reference)
; #define LAS __attribute__((address_space(3)))
; __device__ __forceinline__ void rw_phaseB(LAS unsigned char* lds, const RwCtx& X, int bh) {
;     int tid = threadIdx.x; asm volatile("" : "+v"(tid));
;     const int wave = tid >> 6, lane = tid & 63, fr = lane & 15, fq = lane >> 4;
;     const int d0 = (wave >> 1) * 16, vb0 = (wave & 1) * 2;
;     f32x4 acc[2]; acc[0] = (f32x4){0.f, 0.f, 0.f, 0.f}; acc[1] = acc[0];
;     const unsigned char* gi = X.RWI + (size_t)bh * NCH * RWI_BYTES;
;     bf16x8 pa[4][2], pn[4][2]; u32x2 rf[4][2], rn[4][2]; f32x4 dc[4], dn[4];
;     ...
; #pragma unroll
;     for (int j = 0; j < 4; ++j) RWB_LOAD(pa[j], rf[j], dc[j], j);
;     for (int c0 = 0; c0 < NCH; c0 += 4) {
; #pragma unroll
;         for (int j = 0; j < 4; ++j) { const int cn = c0 + 4 + j;
;             if (cn < NCH) RWB_LOAD(pn[j], rn[j], dn[j], cn);
;             else { pn[j][0] = pa[j][0]; pn[j][1] = pa[j][1]; rn[j][0] = rf[j][0]; rn[j][1] = rf[j][1]; dn[j] = dc[j]; } }
.LBB0_1163:
	s_or_b64 exec, exec, s[6:7]
	v_readlane_b32 s0, v253, 42
	v_readlane_b32 s1, v253, 43
	s_and_b64 vcc, exec, s[0:1]
	s_sub_i32 s0, s94, 127
	s_cmp_lt_u32 s2, s0
	s_cbranch_scc1 .LBB0_1187
	v_lshrrev_b32_e32 v8, 6, v226
	v_and_b32_e32 v14, 15, v226
	v_readfirstlane_b32 s7, v8
	v_bfe_u32 v15, v226, 4, 2
	s_sub_i32 s6, s94, 127
	s_sub_i32 s6, s2, s6
	s_mul_i32 s8, s7, 127
	s_add_i32 s6, s6, s8
	s_cmp_gt_u32 s6, 127
	s_cbranch_scc1 .LBB0_1186
	s_lshr_b32 s7, s6, 2
	s_and_b32 s8, s6, 3
	s_add_u32 s0, s92, 0x6ff4a000
	s_addc_u32 s1, s93, 0
	s_mul_i32 s34, s7, 0x410100
	s_add_u32 s0, s0, s34
	s_addc_u32 s1, s1, 0
	s_mul_i32 s6, s7, 0x102000
	s_add_u32 s34, s92, 0x7814c000
	s_addc_u32 s35, s93, 0
	s_add_u32 s34, s34, s6
	s_addc_u32 s35, s35, 0
	v_mov_b32_e32 v41, 0
	v_lshlrev_b32_e32 v40, 7, v14
	v_lshl_add_u32 v40, v15, 4, v40
	v_lshl_add_u64 v[0:1], s[0:1], 0, v[40:41]
	s_mov_b64 s[100:101], 0x1000
	v_lshl_add_u64 v[2:3], v[0:1], 0, s[100:101]
	s_lshl_b32 s6, s8, 6
	v_and_b32_e32 v40, 63, v226
	v_add_u32_e32 v40, s6, v40
	v_lshlrev_b32_e32 v40, 3, v40
	v_add_u32_e32 v40, 0x2000, v40
	v_lshl_add_u64 v[4:5], s[0:1], 0, v[40:41]
	v_lshl_add_u64 v[6:7], v[4:5], 0, s[100:101]
	v_lshlrev_b32_e32 v40, 4, v15
	v_add_u32_e32 v40, 0x4000, v40
	v_lshl_add_u64 v[10:11], s[0:1], 0, v[40:41]
	s_lshl_b32 s6, s8, 4
	v_add_u32_e32 v40, s6, v14
	v_lshlrev_b32_e32 v40, 7, v40
	v_lshl_add_u32 v40, v15, 3, v40
	v_lshl_add_u64 v[12:13], s[34:35], 0, v[40:41]
	v_mov_b32_e32 v16, 0
	v_mov_b32_e32 v17, 0
	v_mov_b32_e32 v18, 0
	v_mov_b32_e32 v19, 0
	v_mov_b32_e32 v20, 0
	v_mov_b32_e32 v21, 0
	v_mov_b32_e32 v22, 0
	v_mov_b32_e32 v23, 0
	v_mov_b32_e32 v24, 0
	v_mov_b32_e32 v25, 0
	v_mov_b32_e32 v26, 0
	v_mov_b32_e32 v27, 0
	v_mov_b32_e32 v28, 0
	v_mov_b32_e32 v29, 0
	v_mov_b32_e32 v30, 0
	v_mov_b32_e32 v31, 0
	global_load_dwordx2 v[80:81], v[4:5], off offset:0
	global_load_dwordx2 v[82:83], v[4:5], off offset:2048
	global_load_dwordx2 v[84:85], v[6:7], off offset:0
	global_load_dwordx2 v[86:87], v[6:7], off offset:2048
	global_load_dwordx4 v[88:91], v[10:11], off offset:0
	global_load_dwordx4 v[92:95], v[10:11], off offset:64
	global_load_dwordx4 v[96:99], v[10:11], off offset:128
	global_load_dwordx4 v[100:103], v[10:11], off offset:192
	v_add_co_u32_e32 v4, vcc, 0x8100, v4
	s_nop 1
	v_addc_co_u32_e32 v5, vcc, 0, v5, vcc
	v_add_co_u32_e32 v6, vcc, 0x8100, v6
	s_nop 1
	v_addc_co_u32_e32 v7, vcc, 0, v7, vcc
	v_add_co_u32_e32 v10, vcc, 0x8100, v10
	s_nop 1
	v_addc_co_u32_e32 v11, vcc, 0, v11, vcc
	global_load_dwordx4 v[48:51], v[0:1], off offset:0
	global_load_dwordx4 v[52:55], v[0:1], off offset:64
	global_load_dwordx4 v[56:59], v[0:1], off offset:2048
	global_load_dwordx4 v[60:63], v[0:1], off offset:2112
	global_load_dwordx4 v[64:67], v[2:3], off offset:0
	global_load_dwordx4 v[68:71], v[2:3], off offset:64
	global_load_dwordx4 v[72:75], v[2:3], off offset:2048
	global_load_dwordx4 v[76:79], v[2:3], off offset:2112
	v_add_co_u32_e32 v0, vcc, 0x8100, v0
	s_nop 1
	v_addc_co_u32_e32 v1, vcc, 0, v1, vcc
	v_add_co_u32_e32 v2, vcc, 0x8100, v2
	s_nop 1
	v_addc_co_u32_e32 v3, vcc, 0, v3, vcc
	global_load_dwordx2 v[136:137], v[4:5], off offset:0
	global_load_dwordx2 v[138:139], v[4:5], off offset:2048
	global_load_dwordx2 v[140:141], v[6:7], off offset:0
	global_load_dwordx2 v[148:149], v[6:7], off offset:2048
	global_load_dwordx4 v[150:153], v[10:11], off offset:0
	global_load_dwordx4 v[154:157], v[10:11], off offset:64
	global_load_dwordx4 v[158:161], v[10:11], off offset:128
	global_load_dwordx4 v[162:165], v[10:11], off offset:192
	v_add_co_u32_e32 v4, vcc, 0x8100, v4
	s_nop 1
	v_addc_co_u32_e32 v5, vcc, 0, v5, vcc
	v_add_co_u32_e32 v6, vcc, 0x8100, v6
	s_nop 1
	v_addc_co_u32_e32 v7, vcc, 0, v7, vcc
	v_add_co_u32_e32 v10, vcc, 0x8100, v10
	s_nop 1
	v_addc_co_u32_e32 v11, vcc, 0, v11, vcc
	global_load_dwordx4 v[104:107], v[0:1], off offset:0
	global_load_dwordx4 v[108:111], v[0:1], off offset:64
	global_load_dwordx4 v[112:115], v[0:1], off offset:2048
	global_load_dwordx4 v[116:119], v[0:1], off offset:2112
	global_load_dwordx4 v[120:123], v[2:3], off offset:0
	global_load_dwordx4 v[124:127], v[2:3], off offset:64
	global_load_dwordx4 v[128:131], v[2:3], off offset:2048
	global_load_dwordx4 v[132:135], v[2:3], off offset:2112
	v_add_co_u32_e32 v0, vcc, 0x8100, v0
	s_nop 1
	v_addc_co_u32_e32 v1, vcc, 0, v1, vcc
	v_add_co_u32_e32 v2, vcc, 0x8100, v2
	s_nop 1
	v_addc_co_u32_e32 v3, vcc, 0, v3, vcc
	global_load_dwordx2 v[198:199], v[4:5], off offset:0
	global_load_dwordx2 v[200:201], v[4:5], off offset:2048
	global_load_dwordx2 v[202:203], v[6:7], off offset:0
	global_load_dwordx2 v[204:205], v[6:7], off offset:2048
	global_load_dwordx4 v[206:209], v[10:11], off offset:0
	global_load_dwordx4 v[210:213], v[10:11], off offset:64
	global_load_dwordx4 v[214:217], v[10:11], off offset:128
	global_load_dwordx4 v[218:221], v[10:11], off offset:192
	v_add_co_u32_e32 v4, vcc, 0x8100, v4
	s_nop 1
	v_addc_co_u32_e32 v5, vcc, 0, v5, vcc
	v_add_co_u32_e32 v6, vcc, 0x8100, v6
	s_nop 1
	v_addc_co_u32_e32 v7, vcc, 0, v7, vcc
	v_add_co_u32_e32 v10, vcc, 0x8100, v10
	s_nop 1
	v_addc_co_u32_e32 v11, vcc, 0, v11, vcc
	global_load_dwordx4 v[166:169], v[0:1], off offset:0
	global_load_dwordx4 v[170:173], v[0:1], off offset:64
	global_load_dwordx4 v[174:177], v[0:1], off offset:2048
	global_load_dwordx4 v[178:181], v[0:1], off offset:2112
	global_load_dwordx4 v[182:185], v[2:3], off offset:0
	global_load_dwordx4 v[186:189], v[2:3], off offset:64
	global_load_dwordx4 v[190:193], v[2:3], off offset:2048
	global_load_dwordx4 v[194:197], v[2:3], off offset:2112
	v_add_co_u32_e32 v0, vcc, 0x8100, v0
	s_nop 1
	v_addc_co_u32_e32 v1, vcc, 0, v1, vcc
	v_add_co_u32_e32 v2, vcc, 0x8100, v2
	s_nop 1
	v_addc_co_u32_e32 v3, vcc, 0, v3, vcc
	s_waitcnt vmcnt(40)
; #define LAS __attribute__((address_space(3)))
; __device__ __forceinline__ unsigned cvt_pk_bf16(float lo, float hi) { const bf16x2_t r = __builtin_convertvector((f32x2){lo, hi}, bf16x2_t); return __builtin_bit_cast(unsigned, r); }
; __device__ __forceinline__ float bflo(unsigned u) { return __uint_as_float(u << 16); }
; __device__ __forceinline__ float bfhi(unsigned u) { return __uint_as_float(u & 0xffff0000u); }
; #define LDS_BAR() do { asm volatile("s_waitcnt lgkmcnt(0)" ::: "memory"); __builtin_amdgcn_s_barrier(); asm volatile("" ::: "memory"); } while (0)
; __device__ __forceinline__ void rw_phaseB(LAS unsigned char* lds, const RwCtx& X, int bh) {
;     ...
;     for (int c0 = 0; c0 < NCH; c0 += 4) {
; #pragma unroll
;         for (int j = 0; j < 4; ++j) { const int cn = c0 + 4 + j;
;             if (cn < NCH) RWB_LOAD(pn[j], rn[j], dn[j], cn);
;             else { pn[j][0] = pa[j][0]; pn[j][1] = pa[j][1]; rn[j][0] = rf[j][0]; rn[j][1] = rf[j][1]; dn[j] = dc[j]; } }
; #pragma unroll
;         for (int j = 0; j < 4; ++j) { const int c = c0 + j;
;             if (c < NCH) {
;                 LAS bf16_t* STb = (LAS bf16_t*)(lds + (c & 1) * 9216);
;                 bf16_t* sg = X.SRW + ((size_t)bh * NCH + c) * 4096;
; #pragma unroll
;                 for (int bi = 0; bi < 2; ++bi) { const int v0 = (vb0 + bi) * 16; u32x2 o; o.x = cvt_pk_bf16(acc[bi][0], acc[bi][1]); o.y = cvt_pk_bf16(acc[bi][2], acc[bi][3]);
;                     *(LAS u32x2*)(STb + (v0 + fr) * 72 + d0 + fq * 4) = o; *(u32x2*)(sg + (v0 + fr) * 64 + d0 + fq * 4) = o; }
;                 LDS_BAR();
; #pragma unroll
;                 for (int bi = 0; bi < 2; ++bi) { const int v0 = (vb0 + bi) * 16;
;                     f32x4 n = (f32x4){dc[j][0] * acc[bi][0] + bflo(rf[j][bi].x), dc[j][1] * acc[bi][1] + bfhi(rf[j][bi].x), dc[j][2] * acc[bi][2] + bflo(rf[j][bi].y), dc[j][3] * acc[bi][3] + bfhi(rf[j][bi].y)};
; #pragma unroll
;                     for (int k = 0; k < 2; ++k) { const bf16x8 fs = *(const LAS bf16x8*)(STb + (v0 + fr) * 72 + k * 32 + fq * 8); n = __builtin_amdgcn_mfma_f32_16x16x32_bf16(pa[j][k], fs, n, 0, 0, 0); }
;                     acc[bi] = n; }
;             } }
; #pragma unroll
;         for (int j = 0; j < 4; ++j) { pa[j][0] = pn[j][0]; pa[j][1] = pn[j][1]; rf[j][0] = rn[j][0]; rf[j][1] = rn[j][1]; dc[j] = dn[j]; }
;     }
	v_cvt_pk_bf16_f32 v32, v16, v17
	v_cvt_pk_bf16_f32 v33, v18, v19
	v_cvt_pk_bf16_f32 v34, v20, v21
	v_cvt_pk_bf16_f32 v35, v22, v23
	v_cvt_pk_bf16_f32 v36, v24, v25
	v_cvt_pk_bf16_f32 v37, v26, v27
	v_cvt_pk_bf16_f32 v38, v28, v29
	v_cvt_pk_bf16_f32 v39, v30, v31
	global_store_dwordx2 v[12:13], v[32:33], off offset:0
	global_store_dwordx2 v[12:13], v[34:35], off offset:32
	global_store_dwordx2 v[12:13], v[36:37], off offset:64
	global_store_dwordx2 v[12:13], v[38:39], off offset:96
	v_lshlrev_b32_e32 v40, 16, v80
	v_and_b32_e32 v41, 0xffff0000, v80
	v_lshlrev_b32_e32 v42, 16, v81
	v_and_b32_e32 v43, 0xffff0000, v81
	v_pk_fma_f32 v[16:17], v[16:17], v[88:89], v[40:41]
	v_pk_fma_f32 v[18:19], v[18:19], v[90:91], v[42:43]
	v_lshlrev_b32_e32 v40, 16, v82
	v_and_b32_e32 v41, 0xffff0000, v82
	v_lshlrev_b32_e32 v42, 16, v83
	v_and_b32_e32 v43, 0xffff0000, v83
	v_pk_fma_f32 v[20:21], v[20:21], v[92:93], v[40:41]
	v_pk_fma_f32 v[22:23], v[22:23], v[94:95], v[42:43]
	v_lshlrev_b32_e32 v40, 16, v84
	v_and_b32_e32 v41, 0xffff0000, v84
	v_lshlrev_b32_e32 v42, 16, v85
	v_and_b32_e32 v43, 0xffff0000, v85
	v_pk_fma_f32 v[24:25], v[24:25], v[96:97], v[40:41]
	v_pk_fma_f32 v[26:27], v[26:27], v[98:99], v[42:43]
	v_lshlrev_b32_e32 v40, 16, v86
	v_and_b32_e32 v41, 0xffff0000, v86
	v_lshlrev_b32_e32 v42, 16, v87
	v_and_b32_e32 v43, 0xffff0000, v87
	v_pk_fma_f32 v[28:29], v[28:29], v[100:101], v[40:41]
	v_pk_fma_f32 v[30:31], v[30:31], v[102:103], v[42:43]
	v_add_co_u32_e32 v12, vcc, 0x2000, v12
	s_nop 1
	v_addc_co_u32_e32 v13, vcc, 0, v13, vcc
	global_load_dwordx2 v[80:81], v[4:5], off offset:0
	global_load_dwordx2 v[82:83], v[4:5], off offset:2048
	global_load_dwordx2 v[84:85], v[6:7], off offset:0
	global_load_dwordx2 v[86:87], v[6:7], off offset:2048
	global_load_dwordx4 v[88:91], v[10:11], off offset:0
	global_load_dwordx4 v[92:95], v[10:11], off offset:64
	global_load_dwordx4 v[96:99], v[10:11], off offset:128
	global_load_dwordx4 v[100:103], v[10:11], off offset:192
	v_add_co_u32_e32 v4, vcc, 0x8100, v4
	s_nop 1
	v_addc_co_u32_e32 v5, vcc, 0, v5, vcc
	v_add_co_u32_e32 v6, vcc, 0x8100, v6
	s_nop 1
	v_addc_co_u32_e32 v7, vcc, 0, v7, vcc
	v_add_co_u32_e32 v10, vcc, 0x8100, v10
	s_nop 1
	v_addc_co_u32_e32 v11, vcc, 0, v11, vcc
	s_waitcnt vmcnt(44)
	v_mfma_f32_16x16x32_bf16 v[16:19], v[48:51], v[32:35], v[16:19]
	v_mfma_f32_16x16x32_bf16 v[20:23], v[56:59], v[32:35], v[20:23]
	v_mfma_f32_16x16x32_bf16 v[24:27], v[64:67], v[32:35], v[24:27]
	v_mfma_f32_16x16x32_bf16 v[28:31], v[72:75], v[32:35], v[28:31]
	v_mfma_f32_16x16x32_bf16 v[16:19], v[52:55], v[36:39], v[16:19]
	v_mfma_f32_16x16x32_bf16 v[20:23], v[60:63], v[36:39], v[20:23]
	v_mfma_f32_16x16x32_bf16 v[24:27], v[68:71], v[36:39], v[24:27]
	v_mfma_f32_16x16x32_bf16 v[28:31], v[76:79], v[36:39], v[28:31]
	global_load_dwordx4 v[48:51], v[0:1], off offset:0
	global_load_dwordx4 v[52:55], v[0:1], off offset:64
	global_load_dwordx4 v[56:59], v[0:1], off offset:2048
	global_load_dwordx4 v[60:63], v[0:1], off offset:2112
	global_load_dwordx4 v[64:67], v[2:3], off offset:0
	global_load_dwordx4 v[68:71], v[2:3], off offset:64
	global_load_dwordx4 v[72:75], v[2:3], off offset:2048
	global_load_dwordx4 v[76:79], v[2:3], off offset:2112
	v_add_co_u32_e32 v0, vcc, 0x8100, v0
	s_nop 1
	v_addc_co_u32_e32 v1, vcc, 0, v1, vcc
	v_add_co_u32_e32 v2, vcc, 0x8100, v2
	s_nop 1
	v_addc_co_u32_e32 v3, vcc, 0, v3, vcc
	s_waitcnt vmcnt(44)
	v_cvt_pk_bf16_f32 v32, v16, v17
	v_cvt_pk_bf16_f32 v33, v18, v19
	v_cvt_pk_bf16_f32 v34, v20, v21
	v_cvt_pk_bf16_f32 v35, v22, v23
	v_cvt_pk_bf16_f32 v36, v24, v25
	v_cvt_pk_bf16_f32 v37, v26, v27
	v_cvt_pk_bf16_f32 v38, v28, v29
	v_cvt_pk_bf16_f32 v39, v30, v31
	global_store_dwordx2 v[12:13], v[32:33], off offset:0
	global_store_dwordx2 v[12:13], v[34:35], off offset:32
	global_store_dwordx2 v[12:13], v[36:37], off offset:64
	global_store_dwordx2 v[12:13], v[38:39], off offset:96
	v_lshlrev_b32_e32 v40, 16, v136
	v_and_b32_e32 v41, 0xffff0000, v136
	v_lshlrev_b32_e32 v42, 16, v137
	v_and_b32_e32 v43, 0xffff0000, v137
	v_pk_fma_f32 v[16:17], v[16:17], v[150:151], v[40:41]
	v_pk_fma_f32 v[18:19], v[18:19], v[152:153], v[42:43]
	v_lshlrev_b32_e32 v40, 16, v138
	v_and_b32_e32 v41, 0xffff0000, v138
	v_lshlrev_b32_e32 v42, 16, v139
	v_and_b32_e32 v43, 0xffff0000, v139
	v_pk_fma_f32 v[20:21], v[20:21], v[154:155], v[40:41]
	v_pk_fma_f32 v[22:23], v[22:23], v[156:157], v[42:43]
	v_lshlrev_b32_e32 v40, 16, v140
	v_and_b32_e32 v41, 0xffff0000, v140
	v_lshlrev_b32_e32 v42, 16, v141
	v_and_b32_e32 v43, 0xffff0000, v141
	v_pk_fma_f32 v[24:25], v[24:25], v[158:159], v[40:41]
	v_pk_fma_f32 v[26:27], v[26:27], v[160:161], v[42:43]
	v_lshlrev_b32_e32 v40, 16, v148
	v_and_b32_e32 v41, 0xffff0000, v148
	v_lshlrev_b32_e32 v42, 16, v149
	v_and_b32_e32 v43, 0xffff0000, v149
	v_pk_fma_f32 v[28:29], v[28:29], v[162:163], v[40:41]
	v_pk_fma_f32 v[30:31], v[30:31], v[164:165], v[42:43]
	v_add_co_u32_e32 v12, vcc, 0x2000, v12
	s_nop 1
	v_addc_co_u32_e32 v13, vcc, 0, v13, vcc
	global_load_dwordx2 v[136:137], v[4:5], off offset:0
	global_load_dwordx2 v[138:139], v[4:5], off offset:2048
	global_load_dwordx2 v[140:141], v[6:7], off offset:0
	global_load_dwordx2 v[148:149], v[6:7], off offset:2048
	global_load_dwordx4 v[150:153], v[10:11], off offset:0
	global_load_dwordx4 v[154:157], v[10:11], off offset:64
	global_load_dwordx4 v[158:161], v[10:11], off offset:128
	global_load_dwordx4 v[162:165], v[10:11], off offset:192
	v_add_co_u32_e32 v4, vcc, 0x8100, v4
	s_nop 1
	v_addc_co_u32_e32 v5, vcc, 0, v5, vcc
	v_add_co_u32_e32 v6, vcc, 0x8100, v6
	s_nop 1
	v_addc_co_u32_e32 v7, vcc, 0, v7, vcc
	v_add_co_u32_e32 v10, vcc, 0x8100, v10
	s_nop 1
	v_addc_co_u32_e32 v11, vcc, 0, v11, vcc
	s_waitcnt vmcnt(48)
; #define LAS __attribute__((address_space(3)))
; __device__ __forceinline__ unsigned cvt_pk_bf16(float lo, float hi) { const bf16x2_t r = __builtin_convertvector((f32x2){lo, hi}, bf16x2_t); return __builtin_bit_cast(unsigned, r); }
; __device__ __forceinline__ float bflo(unsigned u) { return __uint_as_float(u << 16); }
; __device__ __forceinline__ float bfhi(unsigned u) { return __uint_as_float(u & 0xffff0000u); }
; #define LDS_BAR() do { asm volatile("s_waitcnt lgkmcnt(0)" ::: "memory"); __builtin_amdgcn_s_barrier(); asm volatile("" ::: "memory"); } while (0)
; __device__ __forceinline__ void rw_phaseB(LAS unsigned char* lds, const RwCtx& X, int bh) {
;     ...
;     for (int c0 = 0; c0 < NCH; c0 += 4) {
; #pragma unroll
;         for (int j = 0; j < 4; ++j) { const int cn = c0 + 4 + j;
;             if (cn < NCH) RWB_LOAD(pn[j], rn[j], dn[j], cn);
;             else { pn[j][0] = pa[j][0]; pn[j][1] = pa[j][1]; rn[j][0] = rf[j][0]; rn[j][1] = rf[j][1]; dn[j] = dc[j]; } }
; #pragma unroll
;         for (int j = 0; j < 4; ++j) { const int c = c0 + j;
;             if (c < NCH) {
;                 LAS bf16_t* STb = (LAS bf16_t*)(lds + (c & 1) * 9216);
;                 bf16_t* sg = X.SRW + ((size_t)bh * NCH + c) * 4096;
; #pragma unroll
;                 for (int bi = 0; bi < 2; ++bi) { const int v0 = (vb0 + bi) * 16; u32x2 o; o.x = cvt_pk_bf16(acc[bi][0], acc[bi][1]); o.y = cvt_pk_bf16(acc[bi][2], acc[bi][3]);
;                     *(LAS u32x2*)(STb + (v0 + fr) * 72 + d0 + fq * 4) = o; *(u32x2*)(sg + (v0 + fr) * 64 + d0 + fq * 4) = o; }
;                 LDS_BAR();
; #pragma unroll
;                 for (int bi = 0; bi < 2; ++bi) { const int v0 = (vb0 + bi) * 16;
;                     f32x4 n = (f32x4){dc[j][0] * acc[bi][0] + bflo(rf[j][bi].x), dc[j][1] * acc[bi][1] + bfhi(rf[j][bi].x), dc[j][2] * acc[bi][2] + bflo(rf[j][bi].y), dc[j][3] * acc[bi][3] + bfhi(rf[j][bi].y)};
; #pragma unroll
;                     for (int k = 0; k < 2; ++k) { const bf16x8 fs = *(const LAS bf16x8*)(STb + (v0 + fr) * 72 + k * 32 + fq * 8); n = __builtin_amdgcn_mfma_f32_16x16x32_bf16(pa[j][k], fs, n, 0, 0, 0); }
;                     acc[bi] = n; }
;             } }
; #pragma unroll
;         for (int j = 0; j < 4; ++j) { pa[j][0] = pn[j][0]; pa[j][1] = pn[j][1]; rf[j][0] = rn[j][0]; rf[j][1] = rn[j][1]; dc[j] = dn[j]; }
;     }
	v_mfma_f32_16x16x32_bf16 v[16:19], v[104:107], v[32:35], v[16:19]
	v_mfma_f32_16x16x32_bf16 v[20:23], v[112:115], v[32:35], v[20:23]
	v_mfma_f32_16x16x32_bf16 v[24:27], v[120:123], v[32:35], v[24:27]
	v_mfma_f32_16x16x32_bf16 v[28:31], v[128:131], v[32:35], v[28:31]
	v_mfma_f32_16x16x32_bf16 v[16:19], v[108:111], v[36:39], v[16:19]
	v_mfma_f32_16x16x32_bf16 v[20:23], v[116:119], v[36:39], v[20:23]
	v_mfma_f32_16x16x32_bf16 v[24:27], v[124:127], v[36:39], v[24:27]
	v_mfma_f32_16x16x32_bf16 v[28:31], v[132:135], v[36:39], v[28:31]
	global_load_dwordx4 v[104:107], v[0:1], off offset:0
	global_load_dwordx4 v[108:111], v[0:1], off offset:64
	global_load_dwordx4 v[112:115], v[0:1], off offset:2048
	global_load_dwordx4 v[116:119], v[0:1], off offset:2112
	global_load_dwordx4 v[120:123], v[2:3], off offset:0
	global_load_dwordx4 v[124:127], v[2:3], off offset:64
	global_load_dwordx4 v[128:131], v[2:3], off offset:2048
	global_load_dwordx4 v[132:135], v[2:3], off offset:2112
	v_add_co_u32_e32 v0, vcc, 0x8100, v0
	s_nop 1
	v_addc_co_u32_e32 v1, vcc, 0, v1, vcc
	v_add_co_u32_e32 v2, vcc, 0x8100, v2
	s_nop 1
	v_addc_co_u32_e32 v3, vcc, 0, v3, vcc
	s_waitcnt vmcnt(48)
	v_cvt_pk_bf16_f32 v32, v16, v17
	v_cvt_pk_bf16_f32 v33, v18, v19
	v_cvt_pk_bf16_f32 v34, v20, v21
	v_cvt_pk_bf16_f32 v35, v22, v23
	v_cvt_pk_bf16_f32 v36, v24, v25
	v_cvt_pk_bf16_f32 v37, v26, v27
	v_cvt_pk_bf16_f32 v38, v28, v29
	v_cvt_pk_bf16_f32 v39, v30, v31
	global_store_dwordx2 v[12:13], v[32:33], off offset:0
	global_store_dwordx2 v[12:13], v[34:35], off offset:32
	global_store_dwordx2 v[12:13], v[36:37], off offset:64
	global_store_dwordx2 v[12:13], v[38:39], off offset:96
	v_lshlrev_b32_e32 v40, 16, v198
	v_and_b32_e32 v41, 0xffff0000, v198
	v_lshlrev_b32_e32 v42, 16, v199
	v_and_b32_e32 v43, 0xffff0000, v199
	v_pk_fma_f32 v[16:17], v[16:17], v[206:207], v[40:41]
	v_pk_fma_f32 v[18:19], v[18:19], v[208:209], v[42:43]
	v_lshlrev_b32_e32 v40, 16, v200
	v_and_b32_e32 v41, 0xffff0000, v200
	v_lshlrev_b32_e32 v42, 16, v201
	v_and_b32_e32 v43, 0xffff0000, v201
	v_pk_fma_f32 v[20:21], v[20:21], v[210:211], v[40:41]
	v_pk_fma_f32 v[22:23], v[22:23], v[212:213], v[42:43]
	v_lshlrev_b32_e32 v40, 16, v202
	v_and_b32_e32 v41, 0xffff0000, v202
	v_lshlrev_b32_e32 v42, 16, v203
	v_and_b32_e32 v43, 0xffff0000, v203
	v_pk_fma_f32 v[24:25], v[24:25], v[214:215], v[40:41]
	v_pk_fma_f32 v[26:27], v[26:27], v[216:217], v[42:43]
	v_lshlrev_b32_e32 v40, 16, v204
	v_and_b32_e32 v41, 0xffff0000, v204
	v_lshlrev_b32_e32 v42, 16, v205
	v_and_b32_e32 v43, 0xffff0000, v205
	v_pk_fma_f32 v[28:29], v[28:29], v[218:219], v[40:41]
	v_pk_fma_f32 v[30:31], v[30:31], v[220:221], v[42:43]
	v_add_co_u32_e32 v12, vcc, 0x2000, v12
	s_nop 1
	v_addc_co_u32_e32 v13, vcc, 0, v13, vcc
	global_load_dwordx2 v[198:199], v[4:5], off offset:0
	global_load_dwordx2 v[200:201], v[4:5], off offset:2048
	global_load_dwordx2 v[202:203], v[6:7], off offset:0
	global_load_dwordx2 v[204:205], v[6:7], off offset:2048
	global_load_dwordx4 v[206:209], v[10:11], off offset:0
	global_load_dwordx4 v[210:213], v[10:11], off offset:64
	global_load_dwordx4 v[214:217], v[10:11], off offset:128
	global_load_dwordx4 v[218:221], v[10:11], off offset:192
	v_add_co_u32_e32 v4, vcc, 0x8100, v4
	s_nop 1
	v_addc_co_u32_e32 v5, vcc, 0, v5, vcc
	v_add_co_u32_e32 v6, vcc, 0x8100, v6
	s_nop 1
	v_addc_co_u32_e32 v7, vcc, 0, v7, vcc
	v_add_co_u32_e32 v10, vcc, 0x8100, v10
	s_nop 1
	v_addc_co_u32_e32 v11, vcc, 0, v11, vcc
	s_waitcnt vmcnt(52)
	v_mfma_f32_16x16x32_bf16 v[16:19], v[166:169], v[32:35], v[16:19]
	v_mfma_f32_16x16x32_bf16 v[20:23], v[174:177], v[32:35], v[20:23]
	v_mfma_f32_16x16x32_bf16 v[24:27], v[182:185], v[32:35], v[24:27]
	v_mfma_f32_16x16x32_bf16 v[28:31], v[190:193], v[32:35], v[28:31]
	v_mfma_f32_16x16x32_bf16 v[16:19], v[170:173], v[36:39], v[16:19]
	v_mfma_f32_16x16x32_bf16 v[20:23], v[178:181], v[36:39], v[20:23]
	v_mfma_f32_16x16x32_bf16 v[24:27], v[186:189], v[36:39], v[24:27]
	v_mfma_f32_16x16x32_bf16 v[28:31], v[194:197], v[36:39], v[28:31]
	global_load_dwordx4 v[166:169], v[0:1], off offset:0
	global_load_dwordx4 v[170:173], v[0:1], off offset:64
	global_load_dwordx4 v[174:177], v[0:1], off offset:2048
	global_load_dwordx4 v[178:181], v[0:1], off offset:2112
	global_load_dwordx4 v[182:185], v[2:3], off offset:0
	global_load_dwordx4 v[186:189], v[2:3], off offset:64
	global_load_dwordx4 v[190:193], v[2:3], off offset:2048
	global_load_dwordx4 v[194:197], v[2:3], off offset:2112
	v_add_co_u32_e32 v0, vcc, 0x8100, v0
	s_nop 1
	v_addc_co_u32_e32 v1, vcc, 0, v1, vcc
	v_add_co_u32_e32 v2, vcc, 0x8100, v2
	s_nop 1
	v_addc_co_u32_e32 v3, vcc, 0, v3, vcc
	s_mov_b32 s6, 41
; #define LAS __attribute__((address_space(3)))
; __device__ __forceinline__ unsigned cvt_pk_bf16(float lo, float hi) { const bf16x2_t r = __builtin_convertvector((f32x2){lo, hi}, bf16x2_t); return __builtin_bit_cast(unsigned, r); }
; __device__ __forceinline__ float bflo(unsigned u) { return __uint_as_float(u << 16); }
; __device__ __forceinline__ float bfhi(unsigned u) { return __uint_as_float(u & 0xffff0000u); }
; #define LDS_BAR() do { asm volatile("s_waitcnt lgkmcnt(0)" ::: "memory"); __builtin_amdgcn_s_barrier(); asm volatile("" ::: "memory"); } while (0)
; __device__ __forceinline__ void rw_phaseB(LAS unsigned char* lds, const RwCtx& X, int bh) {
;     ...
;     for (int c0 = 0; c0 < NCH; c0 += 4) {
; #pragma unroll
;         for (int j = 0; j < 4; ++j) { const int cn = c0 + 4 + j;
;             if (cn < NCH) RWB_LOAD(pn[j], rn[j], dn[j], cn);
;             else { pn[j][0] = pa[j][0]; pn[j][1] = pa[j][1]; rn[j][0] = rf[j][0]; rn[j][1] = rf[j][1]; dn[j] = dc[j]; } }
; #pragma unroll
;         for (int j = 0; j < 4; ++j) { const int c = c0 + j;
;             if (c < NCH) {
;                 LAS bf16_t* STb = (LAS bf16_t*)(lds + (c & 1) * 9216);
;                 bf16_t* sg = X.SRW + ((size_t)bh * NCH + c) * 4096;
; #pragma unroll
;                 for (int bi = 0; bi < 2; ++bi) { const int v0 = (vb0 + bi) * 16; u32x2 o; o.x = cvt_pk_bf16(acc[bi][0], acc[bi][1]); o.y = cvt_pk_bf16(acc[bi][2], acc[bi][3]);
;                     *(LAS u32x2*)(STb + (v0 + fr) * 72 + d0 + fq * 4) = o; *(u32x2*)(sg + (v0 + fr) * 64 + d0 + fq * 4) = o; }
;                 LDS_BAR();
; #pragma unroll
;                 for (int bi = 0; bi < 2; ++bi) { const int v0 = (vb0 + bi) * 16;
;                     f32x4 n = (f32x4){dc[j][0] * acc[bi][0] + bflo(rf[j][bi].x), dc[j][1] * acc[bi][1] + bfhi(rf[j][bi].x), dc[j][2] * acc[bi][2] + bflo(rf[j][bi].y), dc[j][3] * acc[bi][3] + bfhi(rf[j][bi].y)};
; #pragma unroll
;                     for (int k = 0; k < 2; ++k) { const bf16x8 fs = *(const LAS bf16x8*)(STb + (v0 + fr) * 72 + k * 32 + fq * 8); n = __builtin_amdgcn_mfma_f32_16x16x32_bf16(pa[j][k], fs, n, 0, 0, 0); }
;                     acc[bi] = n; }
;             } }
; #pragma unroll
;         for (int j = 0; j < 4; ++j) { pa[j][0] = pn[j][0]; pa[j][1] = pn[j][1]; rf[j][0] = rn[j][0]; rf[j][1] = rn[j][1]; dc[j] = dn[j]; }
;     }
.Lrwb_loop:
	s_waitcnt vmcnt(48)
	v_cvt_pk_bf16_f32 v32, v16, v17
	v_cvt_pk_bf16_f32 v33, v18, v19
	v_cvt_pk_bf16_f32 v34, v20, v21
	v_cvt_pk_bf16_f32 v35, v22, v23
	v_cvt_pk_bf16_f32 v36, v24, v25
	v_cvt_pk_bf16_f32 v37, v26, v27
	v_cvt_pk_bf16_f32 v38, v28, v29
	v_cvt_pk_bf16_f32 v39, v30, v31
	global_store_dwordx2 v[12:13], v[32:33], off offset:0
	global_store_dwordx2 v[12:13], v[34:35], off offset:32
	global_store_dwordx2 v[12:13], v[36:37], off offset:64
	global_store_dwordx2 v[12:13], v[38:39], off offset:96
	v_lshlrev_b32_e32 v40, 16, v80
	v_and_b32_e32 v41, 0xffff0000, v80
	v_lshlrev_b32_e32 v42, 16, v81
	v_and_b32_e32 v43, 0xffff0000, v81
	v_pk_fma_f32 v[16:17], v[16:17], v[88:89], v[40:41]
	v_pk_fma_f32 v[18:19], v[18:19], v[90:91], v[42:43]
	v_lshlrev_b32_e32 v40, 16, v82
	v_and_b32_e32 v41, 0xffff0000, v82
	v_lshlrev_b32_e32 v42, 16, v83
	v_and_b32_e32 v43, 0xffff0000, v83
	v_pk_fma_f32 v[20:21], v[20:21], v[92:93], v[40:41]
	v_pk_fma_f32 v[22:23], v[22:23], v[94:95], v[42:43]
	v_lshlrev_b32_e32 v40, 16, v84
	v_and_b32_e32 v41, 0xffff0000, v84
	v_lshlrev_b32_e32 v42, 16, v85
	v_and_b32_e32 v43, 0xffff0000, v85
	v_pk_fma_f32 v[24:25], v[24:25], v[96:97], v[40:41]
	v_pk_fma_f32 v[26:27], v[26:27], v[98:99], v[42:43]
	v_lshlrev_b32_e32 v40, 16, v86
	v_and_b32_e32 v41, 0xffff0000, v86
	v_lshlrev_b32_e32 v42, 16, v87
	v_and_b32_e32 v43, 0xffff0000, v87
	v_pk_fma_f32 v[28:29], v[28:29], v[100:101], v[40:41]
	v_pk_fma_f32 v[30:31], v[30:31], v[102:103], v[42:43]
	v_add_co_u32_e32 v12, vcc, 0x2000, v12
	s_nop 1
	v_addc_co_u32_e32 v13, vcc, 0, v13, vcc
	global_load_dwordx2 v[80:81], v[4:5], off offset:0
	global_load_dwordx2 v[82:83], v[4:5], off offset:2048
	global_load_dwordx2 v[84:85], v[6:7], off offset:0
	global_load_dwordx2 v[86:87], v[6:7], off offset:2048
	global_load_dwordx4 v[88:91], v[10:11], off offset:0
	global_load_dwordx4 v[92:95], v[10:11], off offset:64
	global_load_dwordx4 v[96:99], v[10:11], off offset:128
	global_load_dwordx4 v[100:103], v[10:11], off offset:192
	v_add_co_u32_e32 v4, vcc, 0x8100, v4
	s_nop 1
	v_addc_co_u32_e32 v5, vcc, 0, v5, vcc
	v_add_co_u32_e32 v6, vcc, 0x8100, v6
	s_nop 1
	v_addc_co_u32_e32 v7, vcc, 0, v7, vcc
	v_add_co_u32_e32 v10, vcc, 0x8100, v10
	s_nop 1
	v_addc_co_u32_e32 v11, vcc, 0, v11, vcc
	s_waitcnt vmcnt(52)
	v_mfma_f32_16x16x32_bf16 v[16:19], v[48:51], v[32:35], v[16:19]
	v_mfma_f32_16x16x32_bf16 v[20:23], v[56:59], v[32:35], v[20:23]
	v_mfma_f32_16x16x32_bf16 v[24:27], v[64:67], v[32:35], v[24:27]
	v_mfma_f32_16x16x32_bf16 v[28:31], v[72:75], v[32:35], v[28:31]
	v_mfma_f32_16x16x32_bf16 v[16:19], v[52:55], v[36:39], v[16:19]
	v_mfma_f32_16x16x32_bf16 v[20:23], v[60:63], v[36:39], v[20:23]
	v_mfma_f32_16x16x32_bf16 v[24:27], v[68:71], v[36:39], v[24:27]
	v_mfma_f32_16x16x32_bf16 v[28:31], v[76:79], v[36:39], v[28:31]
	global_load_dwordx4 v[48:51], v[0:1], off offset:0
	global_load_dwordx4 v[52:55], v[0:1], off offset:64
	global_load_dwordx4 v[56:59], v[0:1], off offset:2048
	global_load_dwordx4 v[60:63], v[0:1], off offset:2112
	global_load_dwordx4 v[64:67], v[2:3], off offset:0
	global_load_dwordx4 v[68:71], v[2:3], off offset:64
	global_load_dwordx4 v[72:75], v[2:3], off offset:2048
	global_load_dwordx4 v[76:79], v[2:3], off offset:2112
	v_add_co_u32_e32 v0, vcc, 0x8100, v0
	s_nop 1
	v_addc_co_u32_e32 v1, vcc, 0, v1, vcc
	v_add_co_u32_e32 v2, vcc, 0x8100, v2
	s_nop 1
	v_addc_co_u32_e32 v3, vcc, 0, v3, vcc
	s_waitcnt vmcnt(48)
	v_cvt_pk_bf16_f32 v32, v16, v17
	v_cvt_pk_bf16_f32 v33, v18, v19
	v_cvt_pk_bf16_f32 v34, v20, v21
	v_cvt_pk_bf16_f32 v35, v22, v23
	v_cvt_pk_bf16_f32 v36, v24, v25
	v_cvt_pk_bf16_f32 v37, v26, v27
	v_cvt_pk_bf16_f32 v38, v28, v29
	v_cvt_pk_bf16_f32 v39, v30, v31
	global_store_dwordx2 v[12:13], v[32:33], off offset:0
	global_store_dwordx2 v[12:13], v[34:35], off offset:32
	global_store_dwordx2 v[12:13], v[36:37], off offset:64
	global_store_dwordx2 v[12:13], v[38:39], off offset:96
	v_lshlrev_b32_e32 v40, 16, v136
	v_and_b32_e32 v41, 0xffff0000, v136
	v_lshlrev_b32_e32 v42, 16, v137
	v_and_b32_e32 v43, 0xffff0000, v137
	v_pk_fma_f32 v[16:17], v[16:17], v[150:151], v[40:41]
	v_pk_fma_f32 v[18:19], v[18:19], v[152:153], v[42:43]
	v_lshlrev_b32_e32 v40, 16, v138
	v_and_b32_e32 v41, 0xffff0000, v138
	v_lshlrev_b32_e32 v42, 16, v139
	v_and_b32_e32 v43, 0xffff0000, v139
	v_pk_fma_f32 v[20:21], v[20:21], v[154:155], v[40:41]
	v_pk_fma_f32 v[22:23], v[22:23], v[156:157], v[42:43]
	v_lshlrev_b32_e32 v40, 16, v140
	v_and_b32_e32 v41, 0xffff0000, v140
	v_lshlrev_b32_e32 v42, 16, v141
	v_and_b32_e32 v43, 0xffff0000, v141
	v_pk_fma_f32 v[24:25], v[24:25], v[158:159], v[40:41]
	v_pk_fma_f32 v[26:27], v[26:27], v[160:161], v[42:43]
	v_lshlrev_b32_e32 v40, 16, v148
	v_and_b32_e32 v41, 0xffff0000, v148
	v_lshlrev_b32_e32 v42, 16, v149
	v_and_b32_e32 v43, 0xffff0000, v149
	v_pk_fma_f32 v[28:29], v[28:29], v[162:163], v[40:41]
	v_pk_fma_f32 v[30:31], v[30:31], v[164:165], v[42:43]
	v_add_co_u32_e32 v12, vcc, 0x2000, v12
	s_nop 1
	v_addc_co_u32_e32 v13, vcc, 0, v13, vcc
	global_load_dwordx2 v[136:137], v[4:5], off offset:0
	global_load_dwordx2 v[138:139], v[4:5], off offset:2048
	global_load_dwordx2 v[140:141], v[6:7], off offset:0
	global_load_dwordx2 v[148:149], v[6:7], off offset:2048
	global_load_dwordx4 v[150:153], v[10:11], off offset:0
	global_load_dwordx4 v[154:157], v[10:11], off offset:64
	global_load_dwordx4 v[158:161], v[10:11], off offset:128
	global_load_dwordx4 v[162:165], v[10:11], off offset:192
	v_add_co_u32_e32 v4, vcc, 0x8100, v4
	s_nop 1
	v_addc_co_u32_e32 v5, vcc, 0, v5, vcc
	v_add_co_u32_e32 v6, vcc, 0x8100, v6
	s_nop 1
	v_addc_co_u32_e32 v7, vcc, 0, v7, vcc
	v_add_co_u32_e32 v10, vcc, 0x8100, v10
	s_nop 1
	v_addc_co_u32_e32 v11, vcc, 0, v11, vcc
	s_waitcnt vmcnt(52)
; #define LAS __attribute__((address_space(3)))
; __device__ __forceinline__ unsigned cvt_pk_bf16(float lo, float hi) { const bf16x2_t r = __builtin_convertvector((f32x2){lo, hi}, bf16x2_t); return __builtin_bit_cast(unsigned, r); }
; __device__ __forceinline__ float bflo(unsigned u) { return __uint_as_float(u << 16); }
; __device__ __forceinline__ float bfhi(unsigned u) { return __uint_as_float(u & 0xffff0000u); }
; #define LDS_BAR() do { asm volatile("s_waitcnt lgkmcnt(0)" ::: "memory"); __builtin_amdgcn_s_barrier(); asm volatile("" ::: "memory"); } while (0)
; __device__ __forceinline__ void rw_phaseB(LAS unsigned char* lds, const RwCtx& X, int bh) {
;     ...
;     for (int c0 = 0; c0 < NCH; c0 += 4) {
; #pragma unroll
;         for (int j = 0; j < 4; ++j) { const int cn = c0 + 4 + j;
;             if (cn < NCH) RWB_LOAD(pn[j], rn[j], dn[j], cn);
;             else { pn[j][0] = pa[j][0]; pn[j][1] = pa[j][1]; rn[j][0] = rf[j][0]; rn[j][1] = rf[j][1]; dn[j] = dc[j]; } }
; #pragma unroll
;         for (int j = 0; j < 4; ++j) { const int c = c0 + j;
;             if (c < NCH) {
;                 LAS bf16_t* STb = (LAS bf16_t*)(lds + (c & 1) * 9216);
;                 bf16_t* sg = X.SRW + ((size_t)bh * NCH + c) * 4096;
; #pragma unroll
;                 for (int bi = 0; bi < 2; ++bi) { const int v0 = (vb0 + bi) * 16; u32x2 o; o.x = cvt_pk_bf16(acc[bi][0], acc[bi][1]); o.y = cvt_pk_bf16(acc[bi][2], acc[bi][3]);
;                     *(LAS u32x2*)(STb + (v0 + fr) * 72 + d0 + fq * 4) = o; *(u32x2*)(sg + (v0 + fr) * 64 + d0 + fq * 4) = o; }
;                 LDS_BAR();
; #pragma unroll
;                 for (int bi = 0; bi < 2; ++bi) { const int v0 = (vb0 + bi) * 16;
;                     f32x4 n = (f32x4){dc[j][0] * acc[bi][0] + bflo(rf[j][bi].x), dc[j][1] * acc[bi][1] + bfhi(rf[j][bi].x), dc[j][2] * acc[bi][2] + bflo(rf[j][bi].y), dc[j][3] * acc[bi][3] + bfhi(rf[j][bi].y)};
; #pragma unroll
;                     for (int k = 0; k < 2; ++k) { const bf16x8 fs = *(const LAS bf16x8*)(STb + (v0 + fr) * 72 + k * 32 + fq * 8); n = __builtin_amdgcn_mfma_f32_16x16x32_bf16(pa[j][k], fs, n, 0, 0, 0); }
;                     acc[bi] = n; }
;             } }
; #pragma unroll
;         for (int j = 0; j < 4; ++j) { pa[j][0] = pn[j][0]; pa[j][1] = pn[j][1]; rf[j][0] = rn[j][0]; rf[j][1] = rn[j][1]; dc[j] = dn[j]; }
;     }
	v_mfma_f32_16x16x32_bf16 v[16:19], v[104:107], v[32:35], v[16:19]
	v_mfma_f32_16x16x32_bf16 v[20:23], v[112:115], v[32:35], v[20:23]
	v_mfma_f32_16x16x32_bf16 v[24:27], v[120:123], v[32:35], v[24:27]
	v_mfma_f32_16x16x32_bf16 v[28:31], v[128:131], v[32:35], v[28:31]
	v_mfma_f32_16x16x32_bf16 v[16:19], v[108:111], v[36:39], v[16:19]
	v_mfma_f32_16x16x32_bf16 v[20:23], v[116:119], v[36:39], v[20:23]
	v_mfma_f32_16x16x32_bf16 v[24:27], v[124:127], v[36:39], v[24:27]
	v_mfma_f32_16x16x32_bf16 v[28:31], v[132:135], v[36:39], v[28:31]
	global_load_dwordx4 v[104:107], v[0:1], off offset:0
	global_load_dwordx4 v[108:111], v[0:1], off offset:64
	global_load_dwordx4 v[112:115], v[0:1], off offset:2048
	global_load_dwordx4 v[116:119], v[0:1], off offset:2112
	global_load_dwordx4 v[120:123], v[2:3], off offset:0
	global_load_dwordx4 v[124:127], v[2:3], off offset:64
	global_load_dwordx4 v[128:131], v[2:3], off offset:2048
	global_load_dwordx4 v[132:135], v[2:3], off offset:2112
	v_add_co_u32_e32 v0, vcc, 0x8100, v0
	s_nop 1
	v_addc_co_u32_e32 v1, vcc, 0, v1, vcc
	v_add_co_u32_e32 v2, vcc, 0x8100, v2
	s_nop 1
	v_addc_co_u32_e32 v3, vcc, 0, v3, vcc
	s_waitcnt vmcnt(48)
	v_cvt_pk_bf16_f32 v32, v16, v17
	v_cvt_pk_bf16_f32 v33, v18, v19
	v_cvt_pk_bf16_f32 v34, v20, v21
	v_cvt_pk_bf16_f32 v35, v22, v23
	v_cvt_pk_bf16_f32 v36, v24, v25
	v_cvt_pk_bf16_f32 v37, v26, v27
	v_cvt_pk_bf16_f32 v38, v28, v29
	v_cvt_pk_bf16_f32 v39, v30, v31
	global_store_dwordx2 v[12:13], v[32:33], off offset:0
	global_store_dwordx2 v[12:13], v[34:35], off offset:32
	global_store_dwordx2 v[12:13], v[36:37], off offset:64
	global_store_dwordx2 v[12:13], v[38:39], off offset:96
	v_lshlrev_b32_e32 v40, 16, v198
	v_and_b32_e32 v41, 0xffff0000, v198
	v_lshlrev_b32_e32 v42, 16, v199
	v_and_b32_e32 v43, 0xffff0000, v199
	v_pk_fma_f32 v[16:17], v[16:17], v[206:207], v[40:41]
	v_pk_fma_f32 v[18:19], v[18:19], v[208:209], v[42:43]
	v_lshlrev_b32_e32 v40, 16, v200
	v_and_b32_e32 v41, 0xffff0000, v200
	v_lshlrev_b32_e32 v42, 16, v201
	v_and_b32_e32 v43, 0xffff0000, v201
	v_pk_fma_f32 v[20:21], v[20:21], v[210:211], v[40:41]
	v_pk_fma_f32 v[22:23], v[22:23], v[212:213], v[42:43]
	v_lshlrev_b32_e32 v40, 16, v202
	v_and_b32_e32 v41, 0xffff0000, v202
	v_lshlrev_b32_e32 v42, 16, v203
	v_and_b32_e32 v43, 0xffff0000, v203
	v_pk_fma_f32 v[24:25], v[24:25], v[214:215], v[40:41]
	v_pk_fma_f32 v[26:27], v[26:27], v[216:217], v[42:43]
	v_lshlrev_b32_e32 v40, 16, v204
	v_and_b32_e32 v41, 0xffff0000, v204
	v_lshlrev_b32_e32 v42, 16, v205
	v_and_b32_e32 v43, 0xffff0000, v205
	v_pk_fma_f32 v[28:29], v[28:29], v[218:219], v[40:41]
	v_pk_fma_f32 v[30:31], v[30:31], v[220:221], v[42:43]
	v_add_co_u32_e32 v12, vcc, 0x2000, v12
	s_nop 1
	v_addc_co_u32_e32 v13, vcc, 0, v13, vcc
	global_load_dwordx2 v[198:199], v[4:5], off offset:0
	global_load_dwordx2 v[200:201], v[4:5], off offset:2048
	global_load_dwordx2 v[202:203], v[6:7], off offset:0
	global_load_dwordx2 v[204:205], v[6:7], off offset:2048
	global_load_dwordx4 v[206:209], v[10:11], off offset:0
	global_load_dwordx4 v[210:213], v[10:11], off offset:64
	global_load_dwordx4 v[214:217], v[10:11], off offset:128
	global_load_dwordx4 v[218:221], v[10:11], off offset:192
	v_add_co_u32_e32 v4, vcc, 0x8100, v4
	s_nop 1
	v_addc_co_u32_e32 v5, vcc, 0, v5, vcc
	v_add_co_u32_e32 v6, vcc, 0x8100, v6
	s_nop 1
	v_addc_co_u32_e32 v7, vcc, 0, v7, vcc
	v_add_co_u32_e32 v10, vcc, 0x8100, v10
	s_nop 1
	v_addc_co_u32_e32 v11, vcc, 0, v11, vcc
	s_waitcnt vmcnt(52)
	v_mfma_f32_16x16x32_bf16 v[16:19], v[166:169], v[32:35], v[16:19]
	v_mfma_f32_16x16x32_bf16 v[20:23], v[174:177], v[32:35], v[20:23]
	v_mfma_f32_16x16x32_bf16 v[24:27], v[182:185], v[32:35], v[24:27]
	v_mfma_f32_16x16x32_bf16 v[28:31], v[190:193], v[32:35], v[28:31]
	v_mfma_f32_16x16x32_bf16 v[16:19], v[170:173], v[36:39], v[16:19]
	v_mfma_f32_16x16x32_bf16 v[20:23], v[178:181], v[36:39], v[20:23]
	v_mfma_f32_16x16x32_bf16 v[24:27], v[186:189], v[36:39], v[24:27]
	v_mfma_f32_16x16x32_bf16 v[28:31], v[194:197], v[36:39], v[28:31]
	global_load_dwordx4 v[166:169], v[0:1], off offset:0
	global_load_dwordx4 v[170:173], v[0:1], off offset:64
	global_load_dwordx4 v[174:177], v[0:1], off offset:2048
	global_load_dwordx4 v[178:181], v[0:1], off offset:2112
	global_load_dwordx4 v[182:185], v[2:3], off offset:0
	global_load_dwordx4 v[186:189], v[2:3], off offset:64
	global_load_dwordx4 v[190:193], v[2:3], off offset:2048
	global_load_dwordx4 v[194:197], v[2:3], off offset:2112
	v_add_co_u32_e32 v0, vcc, 0x8100, v0
	s_nop 1
	v_addc_co_u32_e32 v1, vcc, 0, v1, vcc
	v_add_co_u32_e32 v2, vcc, 0x8100, v2
	s_nop 1
	v_addc_co_u32_e32 v3, vcc, 0, v3, vcc
	s_sub_i32 s6, s6, 1
	s_cmp_lg_u32 s6, 0
	s_cbranch_scc1 .Lrwb_loop
; #define LAS __attribute__((address_space(3)))
; __device__ __forceinline__ unsigned cvt_pk_bf16(float lo, float hi) { const bf16x2_t r = __builtin_convertvector((f32x2){lo, hi}, bf16x2_t); return __builtin_bit_cast(unsigned, r); }
; __device__ __forceinline__ float bflo(unsigned u) { return __uint_as_float(u << 16); }
; __device__ __forceinline__ float bfhi(unsigned u) { return __uint_as_float(u & 0xffff0000u); }
; #define LDS_BAR() do { asm volatile("s_waitcnt lgkmcnt(0)" ::: "memory"); __builtin_amdgcn_s_barrier(); asm volatile("" ::: "memory"); } while (0)
; __device__ __forceinline__ void rw_phaseB(LAS unsigned char* lds, const RwCtx& X, int bh) {
;     ...
;     for (int c0 = 0; c0 < NCH; c0 += 4) {
; #pragma unroll
;         for (int j = 0; j < 4; ++j) { const int cn = c0 + 4 + j;
;             if (cn < NCH) RWB_LOAD(pn[j], rn[j], dn[j], cn);
;             else { pn[j][0] = pa[j][0]; pn[j][1] = pa[j][1]; rn[j][0] = rf[j][0]; rn[j][1] = rf[j][1]; dn[j] = dc[j]; } }
; #pragma unroll
;         for (int j = 0; j < 4; ++j) { const int c = c0 + j;
;             if (c < NCH) {
;                 LAS bf16_t* STb = (LAS bf16_t*)(lds + (c & 1) * 9216);
;                 bf16_t* sg = X.SRW + ((size_t)bh * NCH + c) * 4096;
; #pragma unroll
;                 for (int bi = 0; bi < 2; ++bi) { const int v0 = (vb0 + bi) * 16; u32x2 o; o.x = cvt_pk_bf16(acc[bi][0], acc[bi][1]); o.y = cvt_pk_bf16(acc[bi][2], acc[bi][3]);
;                     *(LAS u32x2*)(STb + (v0 + fr) * 72 + d0 + fq * 4) = o; *(u32x2*)(sg + (v0 + fr) * 64 + d0 + fq * 4) = o; }
;                 LDS_BAR();
; #pragma unroll
;                 for (int bi = 0; bi < 2; ++bi) { const int v0 = (vb0 + bi) * 16;
;                     f32x4 n = (f32x4){dc[j][0] * acc[bi][0] + bflo(rf[j][bi].x), dc[j][1] * acc[bi][1] + bfhi(rf[j][bi].x), dc[j][2] * acc[bi][2] + bflo(rf[j][bi].y), dc[j][3] * acc[bi][3] + bfhi(rf[j][bi].y)};
; #pragma unroll
;                     for (int k = 0; k < 2; ++k) { const bf16x8 fs = *(const LAS bf16x8*)(STb + (v0 + fr) * 72 + k * 32 + fq * 8); n = __builtin_amdgcn_mfma_f32_16x16x32_bf16(pa[j][k], fs, n, 0, 0, 0); }
;                     acc[bi] = n; }
;             } }
; #pragma unroll
;         for (int j = 0; j < 4; ++j) { pa[j][0] = pn[j][0]; pa[j][1] = pn[j][1]; rf[j][0] = rn[j][0]; rf[j][1] = rn[j][1]; dc[j] = dn[j]; }
;     }
;     ...
;     LDS_BAR();
	s_waitcnt vmcnt(48)
	v_cvt_pk_bf16_f32 v32, v16, v17
	v_cvt_pk_bf16_f32 v33, v18, v19
	v_cvt_pk_bf16_f32 v34, v20, v21
	v_cvt_pk_bf16_f32 v35, v22, v23
	v_cvt_pk_bf16_f32 v36, v24, v25
	v_cvt_pk_bf16_f32 v37, v26, v27
	v_cvt_pk_bf16_f32 v38, v28, v29
	v_cvt_pk_bf16_f32 v39, v30, v31
	global_store_dwordx2 v[12:13], v[32:33], off offset:0
	global_store_dwordx2 v[12:13], v[34:35], off offset:32
	global_store_dwordx2 v[12:13], v[36:37], off offset:64
	global_store_dwordx2 v[12:13], v[38:39], off offset:96
	v_lshlrev_b32_e32 v40, 16, v80
	v_and_b32_e32 v41, 0xffff0000, v80
	v_lshlrev_b32_e32 v42, 16, v81
	v_and_b32_e32 v43, 0xffff0000, v81
	v_pk_fma_f32 v[16:17], v[16:17], v[88:89], v[40:41]
	v_pk_fma_f32 v[18:19], v[18:19], v[90:91], v[42:43]
	v_lshlrev_b32_e32 v40, 16, v82
	v_and_b32_e32 v41, 0xffff0000, v82
	v_lshlrev_b32_e32 v42, 16, v83
	v_and_b32_e32 v43, 0xffff0000, v83
	v_pk_fma_f32 v[20:21], v[20:21], v[92:93], v[40:41]
	v_pk_fma_f32 v[22:23], v[22:23], v[94:95], v[42:43]
	v_lshlrev_b32_e32 v40, 16, v84
	v_and_b32_e32 v41, 0xffff0000, v84
	v_lshlrev_b32_e32 v42, 16, v85
	v_and_b32_e32 v43, 0xffff0000, v85
	v_pk_fma_f32 v[24:25], v[24:25], v[96:97], v[40:41]
	v_pk_fma_f32 v[26:27], v[26:27], v[98:99], v[42:43]
	v_lshlrev_b32_e32 v40, 16, v86
	v_and_b32_e32 v41, 0xffff0000, v86
	v_lshlrev_b32_e32 v42, 16, v87
	v_and_b32_e32 v43, 0xffff0000, v87
	v_pk_fma_f32 v[28:29], v[28:29], v[100:101], v[40:41]
	v_pk_fma_f32 v[30:31], v[30:31], v[102:103], v[42:43]
	v_add_co_u32_e32 v12, vcc, 0x2000, v12
	s_nop 1
	v_addc_co_u32_e32 v13, vcc, 0, v13, vcc
	s_waitcnt vmcnt(44)
	v_mfma_f32_16x16x32_bf16 v[16:19], v[48:51], v[32:35], v[16:19]
	v_mfma_f32_16x16x32_bf16 v[20:23], v[56:59], v[32:35], v[20:23]
	v_mfma_f32_16x16x32_bf16 v[24:27], v[64:67], v[32:35], v[24:27]
	v_mfma_f32_16x16x32_bf16 v[28:31], v[72:75], v[32:35], v[28:31]
	v_mfma_f32_16x16x32_bf16 v[16:19], v[52:55], v[36:39], v[16:19]
	v_mfma_f32_16x16x32_bf16 v[20:23], v[60:63], v[36:39], v[20:23]
	v_mfma_f32_16x16x32_bf16 v[24:27], v[68:71], v[36:39], v[24:27]
	v_mfma_f32_16x16x32_bf16 v[28:31], v[76:79], v[36:39], v[28:31]
	s_nop 7
	s_waitcnt vmcnt(32)
	v_cvt_pk_bf16_f32 v32, v16, v17
	v_cvt_pk_bf16_f32 v33, v18, v19
	v_cvt_pk_bf16_f32 v34, v20, v21
	v_cvt_pk_bf16_f32 v35, v22, v23
	v_cvt_pk_bf16_f32 v36, v24, v25
	v_cvt_pk_bf16_f32 v37, v26, v27
	v_cvt_pk_bf16_f32 v38, v28, v29
	v_cvt_pk_bf16_f32 v39, v30, v31
	global_store_dwordx2 v[12:13], v[32:33], off offset:0
	global_store_dwordx2 v[12:13], v[34:35], off offset:32
	global_store_dwordx2 v[12:13], v[36:37], off offset:64
	global_store_dwordx2 v[12:13], v[38:39], off offset:96
	v_lshlrev_b32_e32 v40, 16, v136
	v_and_b32_e32 v41, 0xffff0000, v136
	v_lshlrev_b32_e32 v42, 16, v137
	v_and_b32_e32 v43, 0xffff0000, v137
	v_pk_fma_f32 v[16:17], v[16:17], v[150:151], v[40:41]
	v_pk_fma_f32 v[18:19], v[18:19], v[152:153], v[42:43]
	v_lshlrev_b32_e32 v40, 16, v138
	v_and_b32_e32 v41, 0xffff0000, v138
	v_lshlrev_b32_e32 v42, 16, v139
	v_and_b32_e32 v43, 0xffff0000, v139
	v_pk_fma_f32 v[20:21], v[20:21], v[154:155], v[40:41]
	v_pk_fma_f32 v[22:23], v[22:23], v[156:157], v[42:43]
	v_lshlrev_b32_e32 v40, 16, v140
	v_and_b32_e32 v41, 0xffff0000, v140
	v_lshlrev_b32_e32 v42, 16, v141
	v_and_b32_e32 v43, 0xffff0000, v141
	v_pk_fma_f32 v[24:25], v[24:25], v[158:159], v[40:41]
	v_pk_fma_f32 v[26:27], v[26:27], v[160:161], v[42:43]
	v_lshlrev_b32_e32 v40, 16, v148
	v_and_b32_e32 v41, 0xffff0000, v148
	v_lshlrev_b32_e32 v42, 16, v149
	v_and_b32_e32 v43, 0xffff0000, v149
	v_pk_fma_f32 v[28:29], v[28:29], v[162:163], v[40:41]
	v_pk_fma_f32 v[30:31], v[30:31], v[164:165], v[42:43]
	v_add_co_u32_e32 v12, vcc, 0x2000, v12
	s_nop 1
	v_addc_co_u32_e32 v13, vcc, 0, v13, vcc
	s_waitcnt vmcnt(28)
	v_mfma_f32_16x16x32_bf16 v[16:19], v[104:107], v[32:35], v[16:19]
	v_mfma_f32_16x16x32_bf16 v[20:23], v[112:115], v[32:35], v[20:23]
	v_mfma_f32_16x16x32_bf16 v[24:27], v[120:123], v[32:35], v[24:27]
	v_mfma_f32_16x16x32_bf16 v[28:31], v[128:131], v[32:35], v[28:31]
	v_mfma_f32_16x16x32_bf16 v[16:19], v[108:111], v[36:39], v[16:19]
	v_mfma_f32_16x16x32_bf16 v[20:23], v[116:119], v[36:39], v[20:23]
	v_mfma_f32_16x16x32_bf16 v[24:27], v[124:127], v[36:39], v[24:27]
	v_mfma_f32_16x16x32_bf16 v[28:31], v[132:135], v[36:39], v[28:31]
	s_nop 7
	s_waitcnt vmcnt(16)
	v_cvt_pk_bf16_f32 v32, v16, v17
	v_cvt_pk_bf16_f32 v33, v18, v19
	v_cvt_pk_bf16_f32 v34, v20, v21
	v_cvt_pk_bf16_f32 v35, v22, v23
	v_cvt_pk_bf16_f32 v36, v24, v25
	v_cvt_pk_bf16_f32 v37, v26, v27
	v_cvt_pk_bf16_f32 v38, v28, v29
	v_cvt_pk_bf16_f32 v39, v30, v31
	global_store_dwordx2 v[12:13], v[32:33], off offset:0
	global_store_dwordx2 v[12:13], v[34:35], off offset:32
	global_store_dwordx2 v[12:13], v[36:37], off offset:64
	global_store_dwordx2 v[12:13], v[38:39], off offset:96
	v_lshlrev_b32_e32 v40, 16, v198
	v_and_b32_e32 v41, 0xffff0000, v198
	v_lshlrev_b32_e32 v42, 16, v199
	v_and_b32_e32 v43, 0xffff0000, v199
	v_pk_fma_f32 v[16:17], v[16:17], v[206:207], v[40:41]
	v_pk_fma_f32 v[18:19], v[18:19], v[208:209], v[42:43]
	v_lshlrev_b32_e32 v40, 16, v200
	v_and_b32_e32 v41, 0xffff0000, v200
	v_lshlrev_b32_e32 v42, 16, v201
	v_and_b32_e32 v43, 0xffff0000, v201
	v_pk_fma_f32 v[20:21], v[20:21], v[210:211], v[40:41]
	v_pk_fma_f32 v[22:23], v[22:23], v[212:213], v[42:43]
	v_lshlrev_b32_e32 v40, 16, v202
	v_and_b32_e32 v41, 0xffff0000, v202
	v_lshlrev_b32_e32 v42, 16, v203
	v_and_b32_e32 v43, 0xffff0000, v203
	v_pk_fma_f32 v[24:25], v[24:25], v[214:215], v[40:41]
	v_pk_fma_f32 v[26:27], v[26:27], v[216:217], v[42:43]
	v_lshlrev_b32_e32 v40, 16, v204
	v_and_b32_e32 v41, 0xffff0000, v204
	v_lshlrev_b32_e32 v42, 16, v205
	v_and_b32_e32 v43, 0xffff0000, v205
	v_pk_fma_f32 v[28:29], v[28:29], v[218:219], v[40:41]
	v_pk_fma_f32 v[30:31], v[30:31], v[220:221], v[42:43]
	v_add_co_u32_e32 v12, vcc, 0x2000, v12
	s_nop 1
	v_addc_co_u32_e32 v13, vcc, 0, v13, vcc
	s_waitcnt vmcnt(12)
	v_mfma_f32_16x16x32_bf16 v[16:19], v[166:169], v[32:35], v[16:19]
	v_mfma_f32_16x16x32_bf16 v[20:23], v[174:177], v[32:35], v[20:23]
	v_mfma_f32_16x16x32_bf16 v[24:27], v[182:185], v[32:35], v[24:27]
	v_mfma_f32_16x16x32_bf16 v[28:31], v[190:193], v[32:35], v[28:31]
	v_mfma_f32_16x16x32_bf16 v[16:19], v[170:173], v[36:39], v[16:19]
	v_mfma_f32_16x16x32_bf16 v[20:23], v[178:181], v[36:39], v[20:23]
	v_mfma_f32_16x16x32_bf16 v[24:27], v[186:189], v[36:39], v[24:27]
	v_mfma_f32_16x16x32_bf16 v[28:31], v[194:197], v[36:39], v[28:31]
	s_nop 7
	s_mov_b64 s[34:35], 0x8000
